# in-projection epilogue rewritten: row factors computed up front (or re-read from the LDS table when the row block repeats), output stores stream without per-group waits
# speedup vs baseline: 1.0319x; 1.0064x over previous
; #define PG8_WAIT_V(n) asm volatile("s_waitcnt vmcnt(" #n ")" ::: "memory")
; #define PG8_BAR __builtin_amdgcn_s_barrier()
; template <class Epi, class Sched, bool ALIGN_EPI = false, bool SP2 = false>
; __device__ __forceinline__ void gemm_phase(PG8_LAS unsigned char* lds, const Gemm g, const Sched& S, const Epi& E) {
;     int tid_ = threadIdx.x; asm volatile("" : "+v"(tid_));
;     const int tid = tid_, wid = __builtin_amdgcn_readfirstlane(tid >> 6), lane = tid & 63, wr = wid >> 2, wc = wid & 3, fr = lane & 15, fq = lane >> 4;
;     const int K = g.K, nt = K / BK;
;     unsigned voffA[2], voffB[2];
; #pragma unroll
;     for (int i = 0; i < 2; ++i) { int R, C; stage_rc(tid * 16 + i * 8192, R, C); const int Rb = Epi::PERM ? ((R & ~31) + perm32(R & 31)) : R;
;         voffA[i] = (unsigned)(R * K + C) * 2u; voffB[i] = (unsigned)(Rb * K + C) * 2u; }
;     const size_t kstep = (size_t)(BK * 2);
;     const size_t hstep = (size_t)HALF * K * 2;
;     const size_t tstep = 2 * hstep;
;     const unsigned ldsw = (unsigned)wid * 1024u;
;     const int aoff = lds_byte(wr * 64 + fr, fq * 8), boff = lds_byte(wc * 32 + fr, fq * 8);
;     ...
;     Unit cur, nxt; int ui = 0;
;     if (!S.next(0, cur)) return;
;     f32x4 acc[2][2][4][2];
; #pragma unroll
;     for (int a = 0; a < 2; ++a)
; #pragma unroll
;         for (int b = 0; b < 2; ++b)
; #pragma unroll
;             for (int m = 0; m < 4; ++m)
; #pragma unroll
;                 for (int n = 0; n < 2; ++n) acc[a][b][m][n] = (f32x4){0.f, 0.f, 0.f, 0.f};
;     bf16x8 At[4][2], B0[2][2], B1[2][2];
;     const char* cA = (const char*)g.A + (size_t)cur.pm * tstep; const char* cB = (const char*)g.Bt + (size_t)cur.pn * tstep;
;     S.a_ready(cur);
;     if constexpr (SP2) {
;         PG8_STAGE(PG8_SB(0, 0), cB, voffB); PG8_STAGE(PG8_SB(0, 1), cB + hstep, voffB); PG8_STAGE(PG8_SA(0, 0), cA, voffA); PG8_STAGE(PG8_SA(0, 1), cA + hstep, voffA);
;         if (wr == 1) PG8_BAR;
;         PG8_WAIT_V(2); PG8_BAR;
;         PG8_STAGE(PG8_SB(1, 0), cB + kstep, voffB); PG8_STAGE(PG8_SA(1, 0), cA + kstep, voffA); PG8_STAGE(PG8_SB(1, 1), cB + hstep + kstep, voffB);
;         PG8_WAIT_V(6); PG8_BAR;
;     } else {
;         PG8_STAGE(PG8_SB(0, 0), cB, voffB); PG8_STAGE(PG8_SA(0, 0), cA, voffA); PG8_STAGE(PG8_SB(0, 1), cB + hstep, voffB); PG8_STAGE(PG8_SA(0, 1), cA + hstep, voffA);
;         if (wr == 1) PG8_BAR;
;         PG8_WAIT_V(4); PG8_BAR;
.LBB0_459:
	s_add_u32 s12, s6, 0x18a00000
	s_addc_u32 s13, s7, 0
	s_lshl_b32 s15, s15, 5
	s_add_i32 s72, s1, 0x18000
	s_and_b32 s19, s15, 0x60
	s_add_i32 s73, s72, s9
	s_lshl_b32 s18, s5, 13
	s_lshl_b32 s15, s19, 7
	v_lshl_add_u64 v[6:7], v[6:7], 0, s[66:67]
	s_mov_b32 m0, s73
	s_add_i32 s74, s73, 0x2000
	s_add_i32 s75, s64, 0x8000
	s_add_i32 s76, s64, 0xa000
	s_waitcnt vmcnt(2)
	s_barrier
	global_load_lds_dwordx4 v[6:7], off
	v_lshl_add_u64 v[4:5], v[4:5], 0, s[66:67]
	s_mov_b32 m0, s74
	s_add_u32 s16, s28, 0x80080
	global_load_lds_dwordx4 v[4:5], off
	v_lshl_add_u64 v[0:1], v[0:1], 0, s[66:67]
	s_mov_b32 m0, s75
	s_addc_u32 s17, s29, 0
	s_add_i32 s77, s1, 0x1c000
	global_load_lds_dwordx4 v[0:1], off
	v_lshl_add_u64 v[0:1], v[2:3], 0, s[66:67]
	s_mov_b32 m0, s76
	s_add_i32 s78, s77, s9
	global_load_lds_dwordx4 v[0:1], off
	v_lshl_add_u64 v[0:1], s[16:17], 0, v[132:133]
	s_mov_b32 m0, s78
	s_add_i32 s79, s78, 0x2000
	global_load_lds_dwordx4 v[0:1], off
	v_lshl_add_u64 v[0:1], s[16:17], 0, v[130:131]
	s_mov_b32 m0, s79
	s_sext_i32_i8 s25, s4
	global_load_lds_dwordx4 v[0:1], off
	v_bfe_u32 v1, v8, 4, 2
	v_and_b32_e32 v0, 15, v8
	v_lshlrev_b32_e32 v2, 4, v1
	v_lshl_or_b32 v142, s5, 6, v0
	v_lshl_or_b32 v0, v0, 6, v2
	v_lshlrev_b32_e32 v2, 2, v8
	v_and_b32_e32 v2, 32, v2
	v_bitop3_b32 v4, v0, s18, v2 bitop3:0xde
	v_bitop3_b32 v143, v0, s15, v2 bitop3:0xde
	v_lshlrev_b32_e32 v0, 2, v1
	v_lshlrev_b32_e32 v128, 5, v1
	v_lshlrev_b32_e32 v1, 14, v14
	v_and_b32_e32 v1, 0x7fff8000, v1
	v_lshl_add_u32 v1, v13, 11, v1
	v_or_b32_e32 v1, v1, v15
	v_lshl_add_u64 v[2:3], s[6:7], 0, v[128:129]
	v_add_lshl_u32 v128, v1, v16, 1
	v_lshlrev_b32_e32 v1, 14, v9
	v_and_b32_e32 v1, 0x7fff8000, v1
	s_mov_b64 s[4:5], 0x40a00000
	v_lshl_add_u32 v1, v10, 11, v1
	s_waitcnt vmcnt(6)
	v_lshl_add_u64 v[134:135], v[2:3], 0, s[4:5]
	s_mov_b64 s[4:5], 0x80080
	v_or_b32_e32 v1, v1, v11
	s_cmpk_lt_u32 s14, 0x100
	v_lshl_add_u64 v[136:137], v[128:129], 0, s[4:5]
	v_add_lshl_u32 v128, v1, v12, 1
	s_cselect_b64 s[14:15], -1, 0
	v_or_b32_e32 v144, 16, v142
	v_or_b32_e32 v145, 32, v142
	v_or_b32_e32 v146, 48, v142
	s_ashr_i32 s80, s0, 31
	s_mov_b32 s9, s47
	v_lshl_add_u64 v[138:139], v[128:129], 0, s[4:5]
	s_mov_b32 s82, 0
	v_add_u32_e32 v147, s1, v4
	s_lshl_b32 s46, s19, 2
	v_lshlrev_b32_e32 v128, 2, v0
	v_writelane_b32 v255, -1, 41
	s_barrier
	s_branch .LBB0_462

; __device__ __forceinline__ float rs_from_partials(const float* SSP, int row, int fq) {
;     const f32x4 a = *(const f32x4*)(SSP + (size_t)row * 32 + 8 * fq), b = *(const f32x4*)(SSP + (size_t)row * 32 + 8 * fq + 4);
;     float s = ((a[0] + a[1]) + (a[2] + a[3])) + ((b[0] + b[1]) + (b[2] + b[3]));
;     s += __shfl_xor(s, 16); s += __shfl_xor(s, 32);
;     return __builtin_amdgcn_rsqf(s * (1.f / 2048.f) + 1e-6f);
;     __device__ __forceinline__ void operator()(const f32x4 (&acc)[2][2][4][2], const Unit& u, int wr, int wc, int fr, int fq) const {
;     ...
;             for (int m = 0; m < 4; ++m) { const int row = u.pm * BM + ai * HALF + wr * 64 + m * 16 + fr; float* rowp = O + (size_t)row * ldc + u.pn * BM + wc * 32 + 4 * fq;
;                 const float rs = SS ? rs_from_partials(SS, row, fq) : 1.f;
.LBB0_468:
	s_lshl_b32 s17, s24, 8
	v_add_u32_e32 v140, s17, v142
	v_mov_b32_e32 v220, 0x22000
	v_lshl_add_u32 v220, v142, 2, v220
	v_readlane_b32 s26, v255, 41
	s_cmp_eq_u32 s26, s24
	s_cbranch_scc1 .Lf32rs_cached
	v_mov_b32_e32 v216, v140
	v_ashrrev_i32_e32 v217, 31, v216
	v_lshlrev_b64 v[218:219], 7, v[216:217]
	v_lshl_add_u64 v[218:219], v[134:135], 0, v[218:219]
	global_load_dwordx4 v[148:151], v[218:219], off
	global_load_dwordx4 v[152:155], v[218:219], off offset:16
	v_add_u32_e32 v216, 16, v140
	v_ashrrev_i32_e32 v217, 31, v216
	v_lshlrev_b64 v[218:219], 7, v[216:217]
	v_lshl_add_u64 v[218:219], v[134:135], 0, v[218:219]
	global_load_dwordx4 v[156:159], v[218:219], off
	global_load_dwordx4 v[160:163], v[218:219], off offset:16
	v_add_u32_e32 v216, 32, v140
	v_ashrrev_i32_e32 v217, 31, v216
	v_lshlrev_b64 v[218:219], 7, v[216:217]
	v_lshl_add_u64 v[218:219], v[134:135], 0, v[218:219]
	global_load_dwordx4 v[164:167], v[218:219], off
	global_load_dwordx4 v[168:171], v[218:219], off offset:16
	v_add_u32_e32 v216, 48, v140
	v_ashrrev_i32_e32 v217, 31, v216
	v_lshlrev_b64 v[218:219], 7, v[216:217]
	v_lshl_add_u64 v[218:219], v[134:135], 0, v[218:219]
	global_load_dwordx4 v[172:175], v[218:219], off
	global_load_dwordx4 v[176:179], v[218:219], off offset:16
	v_add_u32_e32 v216, 128, v140
	v_ashrrev_i32_e32 v217, 31, v216
	v_lshlrev_b64 v[218:219], 7, v[216:217]
	v_lshl_add_u64 v[218:219], v[134:135], 0, v[218:219]
	global_load_dwordx4 v[180:183], v[218:219], off
	global_load_dwordx4 v[184:187], v[218:219], off offset:16
	v_add_u32_e32 v216, 144, v140
	v_ashrrev_i32_e32 v217, 31, v216
	v_lshlrev_b64 v[218:219], 7, v[216:217]
	v_lshl_add_u64 v[218:219], v[134:135], 0, v[218:219]
	global_load_dwordx4 v[188:191], v[218:219], off
	global_load_dwordx4 v[192:195], v[218:219], off offset:16
	v_add_u32_e32 v216, 160, v140
	v_ashrrev_i32_e32 v217, 31, v216
	v_lshlrev_b64 v[218:219], 7, v[216:217]
	v_lshl_add_u64 v[218:219], v[134:135], 0, v[218:219]
	global_load_dwordx4 v[196:199], v[218:219], off
	global_load_dwordx4 v[200:203], v[218:219], off offset:16
	v_add_u32_e32 v216, 176, v140
	v_ashrrev_i32_e32 v217, 31, v216
	v_lshlrev_b64 v[218:219], 7, v[216:217]
	v_lshl_add_u64 v[218:219], v[134:135], 0, v[218:219]
	global_load_dwordx4 v[208:211], v[218:219], off
	global_load_dwordx4 v[212:215], v[218:219], off offset:16
	v_and_b32_e32 v221, 64, v254
	v_add_u32_e32 v221, 64, v221
	v_xor_b32_e32 v141, 16, v254
	v_cmp_lt_i32_e32 vcc, v141, v221
	v_cndmask_b32_e32 v141, v254, v141, vcc
	v_lshlrev_b32_e32 v204, 2, v141
	v_xor_b32_e32 v141, 32, v254
	v_cmp_lt_i32_e32 vcc, v141, v221
	v_cndmask_b32_e32 v141, v254, v141, vcc
	v_lshlrev_b32_e32 v141, 2, v141
	s_waitcnt vmcnt(14)
	v_add_f32_e32 v148, v148, v149
	v_add_f32_e32 v150, v150, v151
	v_add_f32_e32 v152, v152, v153
	v_add_f32_e32 v154, v154, v155
	v_add_f32_e32 v148, v148, v150
	v_add_f32_e32 v152, v152, v154
	v_add_f32_e32 v148, v148, v152
	ds_bpermute_b32 v149, v204, v148
	s_waitcnt vmcnt(12)
	v_add_f32_e32 v156, v156, v157
	v_add_f32_e32 v158, v158, v159
	v_add_f32_e32 v160, v160, v161
	v_add_f32_e32 v162, v162, v163
	v_add_f32_e32 v156, v156, v158
	v_add_f32_e32 v160, v160, v162
	v_add_f32_e32 v156, v156, v160
	ds_bpermute_b32 v157, v204, v156
	s_waitcnt vmcnt(10)
	v_add_f32_e32 v164, v164, v165
	v_add_f32_e32 v166, v166, v167
	v_add_f32_e32 v168, v168, v169
	v_add_f32_e32 v170, v170, v171
	v_add_f32_e32 v164, v164, v166
	v_add_f32_e32 v168, v168, v170
	v_add_f32_e32 v164, v164, v168
	ds_bpermute_b32 v165, v204, v164
	s_waitcnt vmcnt(8)
	v_add_f32_e32 v172, v172, v173
	v_add_f32_e32 v174, v174, v175
	v_add_f32_e32 v176, v176, v177
	v_add_f32_e32 v178, v178, v179
	v_add_f32_e32 v172, v172, v174
	v_add_f32_e32 v176, v176, v178
	v_add_f32_e32 v172, v172, v176
	ds_bpermute_b32 v173, v204, v172
	s_waitcnt vmcnt(6)
	v_add_f32_e32 v180, v180, v181
	v_add_f32_e32 v182, v182, v183
	v_add_f32_e32 v184, v184, v185
	v_add_f32_e32 v186, v186, v187
	v_add_f32_e32 v180, v180, v182
	v_add_f32_e32 v184, v184, v186
	v_add_f32_e32 v180, v180, v184
	ds_bpermute_b32 v181, v204, v180
	s_waitcnt vmcnt(4)
	v_add_f32_e32 v188, v188, v189
	v_add_f32_e32 v190, v190, v191
	v_add_f32_e32 v192, v192, v193
	v_add_f32_e32 v194, v194, v195
	v_add_f32_e32 v188, v188, v190
	v_add_f32_e32 v192, v192, v194
	v_add_f32_e32 v188, v188, v192
	ds_bpermute_b32 v189, v204, v188
	s_waitcnt vmcnt(2)
	v_add_f32_e32 v196, v196, v197
	v_add_f32_e32 v198, v198, v199
	v_add_f32_e32 v200, v200, v201
	v_add_f32_e32 v202, v202, v203
	v_add_f32_e32 v196, v196, v198
	v_add_f32_e32 v200, v200, v202
	v_add_f32_e32 v196, v196, v200
	ds_bpermute_b32 v197, v204, v196
	s_waitcnt vmcnt(0)
	v_add_f32_e32 v208, v208, v209
	v_add_f32_e32 v210, v210, v211
	v_add_f32_e32 v212, v212, v213
	v_add_f32_e32 v214, v214, v215
	v_add_f32_e32 v208, v208, v210
	v_add_f32_e32 v212, v212, v214
	v_add_f32_e32 v208, v208, v212
	ds_bpermute_b32 v209, v204, v208
	s_waitcnt lgkmcnt(7)
	v_add_f32_e32 v148, v148, v149
	s_waitcnt lgkmcnt(6)
	v_add_f32_e32 v156, v156, v157
	s_waitcnt lgkmcnt(5)
	v_add_f32_e32 v164, v164, v165
	s_waitcnt lgkmcnt(4)
	v_add_f32_e32 v172, v172, v173
	s_waitcnt lgkmcnt(3)
	v_add_f32_e32 v180, v180, v181
	s_waitcnt lgkmcnt(2)
	v_add_f32_e32 v188, v188, v189
	s_waitcnt lgkmcnt(1)
	v_add_f32_e32 v196, v196, v197
	s_waitcnt lgkmcnt(0)
	v_add_f32_e32 v208, v208, v209
	ds_bpermute_b32 v149, v141, v148
	ds_bpermute_b32 v157, v141, v156
	ds_bpermute_b32 v165, v141, v164
	ds_bpermute_b32 v173, v141, v172
	ds_bpermute_b32 v181, v141, v180
	ds_bpermute_b32 v189, v141, v188
	ds_bpermute_b32 v197, v141, v196
	ds_bpermute_b32 v209, v141, v208
	s_waitcnt lgkmcnt(7)
	v_add_f32_e32 v148, v148, v149
	s_waitcnt lgkmcnt(6)
	v_add_f32_e32 v156, v156, v157
	s_waitcnt lgkmcnt(5)
	v_add_f32_e32 v164, v164, v165
	s_waitcnt lgkmcnt(4)
	v_add_f32_e32 v172, v172, v173
	s_waitcnt lgkmcnt(3)
	v_add_f32_e32 v180, v180, v181
	s_waitcnt lgkmcnt(2)
	v_add_f32_e32 v188, v188, v189
	s_waitcnt lgkmcnt(1)
	v_add_f32_e32 v196, v196, v197
	s_waitcnt lgkmcnt(0)
	v_add_f32_e32 v208, v208, v209
	v_fmamk_f32 v148, v148, 0x3a000000, v241
	v_fmamk_f32 v156, v156, 0x3a000000, v241
	v_fmamk_f32 v164, v164, 0x3a000000, v241
	v_fmamk_f32 v172, v172, 0x3a000000, v241
	v_fmamk_f32 v180, v180, 0x3a000000, v241
	v_fmamk_f32 v188, v188, 0x3a000000, v241
	v_fmamk_f32 v196, v196, 0x3a000000, v241
	v_fmamk_f32 v208, v208, 0x3a000000, v241
	v_rsq_f32_e32 v148, v148
	v_rsq_f32_e32 v156, v156
	v_rsq_f32_e32 v164, v164
	v_rsq_f32_e32 v172, v172
	v_rsq_f32_e32 v180, v180
	v_rsq_f32_e32 v188, v188
	v_rsq_f32_e32 v196, v196
	v_rsq_f32_e32 v208, v208
	v_writelane_b32 v255, s24, 41
	ds_write_b32 v220, v148
	ds_write_b32 v220, v156 offset:64
	ds_write_b32 v220, v164 offset:128
	ds_write_b32 v220, v172 offset:192
	ds_write_b32 v220, v180 offset:512
	ds_write_b32 v220, v188 offset:576
	ds_write_b32 v220, v196 offset:640
	ds_write_b32 v220, v208 offset:704
	s_branch .Lf32rs_done
;     __device__ __forceinline__ void operator()(const f32x4 (&acc)[2][2][4][2], const Unit& u, int wr, int wc, int fr, int fq) const {
;     ...
;             for (int m = 0; m < 4; ++m) { const int row = u.pm * BM + ai * HALF + wr * 64 + m * 16 + fr; float* rowp = O + (size_t)row * ldc + u.pn * BM + wc * 32 + 4 * fq;
;                 const float rs = SS ? rs_from_partials(SS, row, fq) : 1.f;
; #pragma unroll
;                 for (int bj = 0; bj < 2; ++bj)
; #pragma unroll
;                     for (int n = 0; n < 2; ++n) *(f32x4*)(rowp + bj * HALF + n * 16) = acc[ai][bj][m][n] * rs; }
.Lf32rs_cached:
	ds_read_b32 v148, v220
	ds_read_b32 v156, v220 offset:64
	ds_read_b32 v164, v220 offset:128
	ds_read_b32 v172, v220 offset:192
	ds_read_b32 v180, v220 offset:512
	ds_read_b32 v188, v220 offset:576
	ds_read_b32 v196, v220 offset:640
	ds_read_b32 v208, v220 offset:704
.Lf32rs_done:
	s_lshl_b32 s24, s25, 8
	s_ashr_i32 s25, s24, 31
	s_lshl_b64 s[24:25], s[24:25], 2
	s_waitcnt lgkmcnt(0)
	v_mov_b32_e32 v216, v140
	v_mad_i64_i32 v[218:219], s[26:27], v216, s37, 0
	v_lshl_add_u64 v[218:219], v[218:219], 2, s[12:13]
	v_lshl_add_u64 v[218:219], v[218:219], 0, s[24:25]
	v_lshl_add_u64 v[218:219], v[218:219], 0, s[46:47]
	v_lshl_add_u64 v[218:219], v[218:219], 0, v[128:129]
	v_pk_mul_f32 v[124:125], v[124:125], v[148:149] op_sel_hi:[1,0]
	v_pk_mul_f32 v[126:127], v[126:127], v[148:149] op_sel_hi:[1,0]
	v_pk_mul_f32 v[120:121], v[120:121], v[148:149] op_sel_hi:[1,0]
	v_pk_mul_f32 v[122:123], v[122:123], v[148:149] op_sel_hi:[1,0]
	v_pk_mul_f32 v[116:117], v[116:117], v[148:149] op_sel_hi:[1,0]
	v_pk_mul_f32 v[118:119], v[118:119], v[148:149] op_sel_hi:[1,0]
	v_pk_mul_f32 v[112:113], v[112:113], v[148:149] op_sel_hi:[1,0]
	v_pk_mul_f32 v[114:115], v[114:115], v[148:149] op_sel_hi:[1,0]
	global_store_dwordx4 v[218:219], v[124:127], off
	global_store_dwordx4 v[218:219], v[120:123], off offset:64
	global_store_dwordx4 v[218:219], v[116:119], off offset:512
	global_store_dwordx4 v[218:219], v[112:115], off offset:576
	v_add_u32_e32 v216, 16, v140
	v_mad_i64_i32 v[204:205], s[26:27], v216, s37, 0
	v_lshl_add_u64 v[204:205], v[204:205], 2, s[12:13]
	v_lshl_add_u64 v[204:205], v[204:205], 0, s[24:25]
	v_lshl_add_u64 v[204:205], v[204:205], 0, s[46:47]
	v_lshl_add_u64 v[204:205], v[204:205], 0, v[128:129]
	v_pk_mul_f32 v[108:109], v[108:109], v[156:157] op_sel_hi:[1,0]
	v_pk_mul_f32 v[110:111], v[110:111], v[156:157] op_sel_hi:[1,0]
	v_pk_mul_f32 v[104:105], v[104:105], v[156:157] op_sel_hi:[1,0]
	v_pk_mul_f32 v[106:107], v[106:107], v[156:157] op_sel_hi:[1,0]
	v_pk_mul_f32 v[100:101], v[100:101], v[156:157] op_sel_hi:[1,0]
	v_pk_mul_f32 v[102:103], v[102:103], v[156:157] op_sel_hi:[1,0]
	v_pk_mul_f32 v[96:97], v[96:97], v[156:157] op_sel_hi:[1,0]
	v_pk_mul_f32 v[98:99], v[98:99], v[156:157] op_sel_hi:[1,0]
	global_store_dwordx4 v[204:205], v[108:111], off
	global_store_dwordx4 v[204:205], v[104:107], off offset:64
	global_store_dwordx4 v[204:205], v[100:103], off offset:512
	global_store_dwordx4 v[204:205], v[96:99], off offset:576
	v_add_u32_e32 v216, 32, v140
	v_mad_i64_i32 v[218:219], s[26:27], v216, s37, 0
	v_lshl_add_u64 v[218:219], v[218:219], 2, s[12:13]
	v_lshl_add_u64 v[218:219], v[218:219], 0, s[24:25]
	v_lshl_add_u64 v[218:219], v[218:219], 0, s[46:47]
	v_lshl_add_u64 v[218:219], v[218:219], 0, v[128:129]
	v_pk_mul_f32 v[92:93], v[92:93], v[164:165] op_sel_hi:[1,0]
	v_pk_mul_f32 v[94:95], v[94:95], v[164:165] op_sel_hi:[1,0]
	v_pk_mul_f32 v[88:89], v[88:89], v[164:165] op_sel_hi:[1,0]
	v_pk_mul_f32 v[90:91], v[90:91], v[164:165] op_sel_hi:[1,0]
	v_pk_mul_f32 v[84:85], v[84:85], v[164:165] op_sel_hi:[1,0]
	v_pk_mul_f32 v[86:87], v[86:87], v[164:165] op_sel_hi:[1,0]
	v_pk_mul_f32 v[80:81], v[80:81], v[164:165] op_sel_hi:[1,0]
	v_pk_mul_f32 v[82:83], v[82:83], v[164:165] op_sel_hi:[1,0]
	global_store_dwordx4 v[218:219], v[92:95], off
	global_store_dwordx4 v[218:219], v[88:91], off offset:64
	global_store_dwordx4 v[218:219], v[84:87], off offset:512
	global_store_dwordx4 v[218:219], v[80:83], off offset:576
	v_add_u32_e32 v216, 48, v140
	v_mad_i64_i32 v[204:205], s[26:27], v216, s37, 0
	v_lshl_add_u64 v[204:205], v[204:205], 2, s[12:13]
	v_lshl_add_u64 v[204:205], v[204:205], 0, s[24:25]
	v_lshl_add_u64 v[204:205], v[204:205], 0, s[46:47]
	v_lshl_add_u64 v[204:205], v[204:205], 0, v[128:129]
	v_pk_mul_f32 v[76:77], v[76:77], v[172:173] op_sel_hi:[1,0]
	v_pk_mul_f32 v[78:79], v[78:79], v[172:173] op_sel_hi:[1,0]
	v_pk_mul_f32 v[72:73], v[72:73], v[172:173] op_sel_hi:[1,0]
	v_pk_mul_f32 v[74:75], v[74:75], v[172:173] op_sel_hi:[1,0]
	v_pk_mul_f32 v[68:69], v[68:69], v[172:173] op_sel_hi:[1,0]
	v_pk_mul_f32 v[70:71], v[70:71], v[172:173] op_sel_hi:[1,0]
	v_pk_mul_f32 v[64:65], v[64:65], v[172:173] op_sel_hi:[1,0]
	v_pk_mul_f32 v[66:67], v[66:67], v[172:173] op_sel_hi:[1,0]
	global_store_dwordx4 v[204:205], v[76:79], off
;     __device__ __forceinline__ void operator()(const f32x4 (&acc)[2][2][4][2], const Unit& u, int wr, int wc, int fr, int fq) const {
;     ...
;             for (int m = 0; m < 4; ++m) { const int row = u.pm * BM + ai * HALF + wr * 64 + m * 16 + fr; float* rowp = O + (size_t)row * ldc + u.pn * BM + wc * 32 + 4 * fq;
;                 const float rs = SS ? rs_from_partials(SS, row, fq) : 1.f;
; #pragma unroll
;                 for (int bj = 0; bj < 2; ++bj)
; #pragma unroll
;                     for (int n = 0; n < 2; ++n) *(f32x4*)(rowp + bj * HALF + n * 16) = acc[ai][bj][m][n] * rs; }
	global_store_dwordx4 v[204:205], v[72:75], off offset:64
	global_store_dwordx4 v[204:205], v[68:71], off offset:512
	global_store_dwordx4 v[204:205], v[64:67], off offset:576
	v_add_u32_e32 v216, 128, v140
	v_mad_i64_i32 v[218:219], s[26:27], v216, s37, 0
	v_lshl_add_u64 v[218:219], v[218:219], 2, s[12:13]
	v_lshl_add_u64 v[218:219], v[218:219], 0, s[24:25]
	v_lshl_add_u64 v[218:219], v[218:219], 0, s[46:47]
	v_lshl_add_u64 v[218:219], v[218:219], 0, v[128:129]
	v_pk_mul_f32 v[60:61], v[60:61], v[180:181] op_sel_hi:[1,0]
	v_pk_mul_f32 v[62:63], v[62:63], v[180:181] op_sel_hi:[1,0]
	v_pk_mul_f32 v[56:57], v[56:57], v[180:181] op_sel_hi:[1,0]
	v_pk_mul_f32 v[58:59], v[58:59], v[180:181] op_sel_hi:[1,0]
	v_pk_mul_f32 v[52:53], v[52:53], v[180:181] op_sel_hi:[1,0]
	v_pk_mul_f32 v[54:55], v[54:55], v[180:181] op_sel_hi:[1,0]
	v_pk_mul_f32 v[48:49], v[48:49], v[180:181] op_sel_hi:[1,0]
	v_pk_mul_f32 v[50:51], v[50:51], v[180:181] op_sel_hi:[1,0]
	global_store_dwordx4 v[218:219], v[60:63], off
	global_store_dwordx4 v[218:219], v[56:59], off offset:64
	global_store_dwordx4 v[218:219], v[52:55], off offset:512
	global_store_dwordx4 v[218:219], v[48:51], off offset:576
	v_add_u32_e32 v216, 144, v140
	v_mad_i64_i32 v[204:205], s[26:27], v216, s37, 0
	v_lshl_add_u64 v[204:205], v[204:205], 2, s[12:13]
	v_lshl_add_u64 v[204:205], v[204:205], 0, s[24:25]
	v_lshl_add_u64 v[204:205], v[204:205], 0, s[46:47]
	v_lshl_add_u64 v[204:205], v[204:205], 0, v[128:129]
	v_pk_mul_f32 v[44:45], v[44:45], v[188:189] op_sel_hi:[1,0]
	v_pk_mul_f32 v[46:47], v[46:47], v[188:189] op_sel_hi:[1,0]
	v_pk_mul_f32 v[40:41], v[40:41], v[188:189] op_sel_hi:[1,0]
	v_pk_mul_f32 v[42:43], v[42:43], v[188:189] op_sel_hi:[1,0]
	v_pk_mul_f32 v[36:37], v[36:37], v[188:189] op_sel_hi:[1,0]
	v_pk_mul_f32 v[38:39], v[38:39], v[188:189] op_sel_hi:[1,0]
	v_pk_mul_f32 v[32:33], v[32:33], v[188:189] op_sel_hi:[1,0]
	v_pk_mul_f32 v[34:35], v[34:35], v[188:189] op_sel_hi:[1,0]
	global_store_dwordx4 v[204:205], v[44:47], off
	global_store_dwordx4 v[204:205], v[40:43], off offset:64
	global_store_dwordx4 v[204:205], v[36:39], off offset:512
	global_store_dwordx4 v[204:205], v[32:35], off offset:576
	v_add_u32_e32 v216, 160, v140
	v_mad_i64_i32 v[218:219], s[26:27], v216, s37, 0
	v_lshl_add_u64 v[218:219], v[218:219], 2, s[12:13]
	v_lshl_add_u64 v[218:219], v[218:219], 0, s[24:25]
	v_lshl_add_u64 v[218:219], v[218:219], 0, s[46:47]
	v_lshl_add_u64 v[218:219], v[218:219], 0, v[128:129]
	v_pk_mul_f32 v[28:29], v[28:29], v[196:197] op_sel_hi:[1,0]
	v_pk_mul_f32 v[30:31], v[30:31], v[196:197] op_sel_hi:[1,0]
	v_pk_mul_f32 v[24:25], v[24:25], v[196:197] op_sel_hi:[1,0]
	v_pk_mul_f32 v[26:27], v[26:27], v[196:197] op_sel_hi:[1,0]
	v_pk_mul_f32 v[20:21], v[20:21], v[196:197] op_sel_hi:[1,0]
	v_pk_mul_f32 v[22:23], v[22:23], v[196:197] op_sel_hi:[1,0]
	v_pk_mul_f32 v[16:17], v[16:17], v[196:197] op_sel_hi:[1,0]
	v_pk_mul_f32 v[18:19], v[18:19], v[196:197] op_sel_hi:[1,0]
	global_store_dwordx4 v[218:219], v[28:31], off
	global_store_dwordx4 v[218:219], v[24:27], off offset:64
	global_store_dwordx4 v[218:219], v[20:23], off offset:512
	global_store_dwordx4 v[218:219], v[16:19], off offset:576
	v_add_u32_e32 v216, 176, v140
	v_mad_i64_i32 v[204:205], s[26:27], v216, s37, 0
	v_lshl_add_u64 v[204:205], v[204:205], 2, s[12:13]
	v_lshl_add_u64 v[204:205], v[204:205], 0, s[24:25]
	v_lshl_add_u64 v[204:205], v[204:205], 0, s[46:47]
	v_lshl_add_u64 v[204:205], v[204:205], 0, v[128:129]
	v_pk_mul_f32 v[12:13], v[12:13], v[208:209] op_sel_hi:[1,0]
	v_pk_mul_f32 v[14:15], v[14:15], v[208:209] op_sel_hi:[1,0]
	v_pk_mul_f32 v[8:9], v[8:9], v[208:209] op_sel_hi:[1,0]
	v_pk_mul_f32 v[10:11], v[10:11], v[208:209] op_sel_hi:[1,0]
	v_pk_mul_f32 v[4:5], v[4:5], v[208:209] op_sel_hi:[1,0]
	v_pk_mul_f32 v[6:7], v[6:7], v[208:209] op_sel_hi:[1,0]
	v_pk_mul_f32 v[0:1], v[0:1], v[208:209] op_sel_hi:[1,0]
	v_pk_mul_f32 v[2:3], v[2:3], v[208:209] op_sel_hi:[1,0]
	global_store_dwordx4 v[204:205], v[12:15], off
	global_store_dwordx4 v[204:205], v[8:11], off offset:64
	global_store_dwordx4 v[204:205], v[4:7], off offset:512
	global_store_dwordx4 v[204:205], v[0:3], off offset:576
	s_andn2_b64 vcc, exec, s[4:5]
	s_mov_b64 s[24:25], -1
	s_cbranch_vccnz .LBB0_461
	s_andn2_b64 vcc, exec, s[10:11]
	s_cbranch_vccnz .LBB0_460
	s_barrier
	s_branch .LBB0_460
